# m3qk: M3 Q/K tiles loaded with a coalesced thread map (16 lanes per 256-B row segment) instead of one row per lane
# speedup vs baseline: 1.0048x; 1.0048x over previous
;   __host__ __device__ __forceinline__ float* G() const { return (float*)(wsl() + OFF_G); }
;   __host__ __device__ __forceinline__ bf16_t* Wgu(int i) const { return (bf16_t*)(wsl() + OFF_FFN + (size_t)i * FFN_STRIDE); }
;   __host__ __device__ __forceinline__ bf16_t* Wd(int i) const { return (bf16_t*)(wsl() + OFF_FFN + (size_t)i * FFN_STRIDE + WGU_B); }
;   __host__ __device__ __forceinline__ bf16_t* Wein() const { return (bf16_t*)(wsl() + OFF_WEIN); }
;   __host__ __device__ __forceinline__ bf16_t* H() const { return (bf16_t*)(wsl() + OFF_H); }
;   __host__ __device__ __forceinline__ bf16_t* ACT() const { return (bf16_t*)(wsl() + OFF_ACT); }
; __device__ __forceinline__ void m3_phase(const Params& p, char* smem) {
;   const int tid = otid(), lane = tid & 63, w = tid >> 6, fr = lane & 15, fq = lane >> 4;
;   bf16_t* Qs = (bf16_t*)smem;
;   bf16_t* Ks = Qs + 64 * 136;
;   bf16_t* Vt = Ks + 64 * 136;
;   bf16_t* Cs = Vt + 128 * 72;
;   bf16_t* Sw = Cs + 128 * 136;
;   float* hs = (float*)(Sw + 64 * 72);
;   float* cs = hs + 64 * 132;
;   float* rt = cs + 64;
;   float* wint = rt + 64;
;   float* emt = wint + 64;
;   float* qn = emt + 64;
;   float* denp = qn + 64;
;   float* ns = denp + 128;
;   bf16_t* MIX = p.H();
; __device__ __forceinline__ void run_phase(const Params& p, int ph, char* smem) {
;     ...
;   switch (kind) {
;     case K_P0: if (!KEN(K_P0)) break; p0_phase(p, smem); break;
;     case K_NORMMOD: if (!KEN(K_NORMMOD)) break; normmod_phase(p, a0, a1, a2); break;
;     case K_FFN_UP: if (!KEN(K_FFN_UP)) break;
;       fe.outb = p.ACT(); fe.ldo = DFF;
;       fast_gemm<EPI_SWIGLU>(p, fe, p.H(), D, p.Wgu(a0), D, 22, a1, smem); break;
;     case K_FFN_DOWN: if (!KEN(K_FFN_DOWN)) break;
;       fe.layer = a0 >> 1; fe.slot = (a0 & 1) ? 8 : 2; fe.scale = 0.5f; fe.xin = a2 ? p.x : nullptr;
;       fast_gemm<EPI_RESID>(p, fe, p.ACT(), DFF, p.Wd(a0), DFF, 4, 1, smem);
;       if (a1) ctx_gemm<EPI_RESID>(p, fe, p.ACT(), DFF, p.Wd(a0), DFF, 0, 16, smem);
;       break;
;     case K_E1: if (!KEN(K_E1)) break; fe.outb = p.ACT(); fe.outf = p.G();
;       fast_gemm<EPI_E1>(p, fe, p.H(), D, p.Wein(), D, 11, 0, smem); break;
;     case K_M1: if (!KEN(K_M1)) break; m1_phase(p, smem); break;
;     case K_M2: if (!KEN(K_M2)) break; m2_phase(p); break;
;     case K_M3: if (!KEN(K_M3)) break; m3_phase(p, smem); break;
.LBB0_478:
	s_andn2_b64 vcc, exec, s[2:3]
	s_cbranch_vccnz .LBB0_1070
	s_and_b32 s2, 0xffff, s18
	v_writelane_b32 v255, s2, 58
	s_cmp_lt_i32 s2, 4
	s_mov_b64 s[2:3], -1
	s_cbranch_scc1 .LBB0_820
	v_readlane_b32 s2, v255, 58
	s_cmp_lt_i32 s2, 6
	s_mov_b64 s[2:3], -1
	s_cbranch_scc1 .LBB0_756
	v_readlane_b32 s2, v255, 58
	s_cmp_gt_i32 s2, 6
	s_mov_b64 s[2:3], -1
	s_cbranch_scc0 .LBB0_550
	v_mov_b32_e32 v32, v164
	s_mov_b32 s4, s82
	s_cmpk_gt_i32 s4, 0x41f
	s_cbranch_scc1 .LBB0_549
	v_and_b32_e32 v13, 64, v231
	v_xor_b32_e32 v12, 1, v231
	v_add_u32_e32 v14, 64, v13
	v_cmp_lt_i32_e32 vcc, v12, v14
	s_waitcnt lgkmcnt(0)
	v_ashrrev_i32_e32 v1, 6, v32
	v_and_b32_e32 v5, 3, v1
	v_cndmask_b32_e32 v12, v231, v12, vcc
	v_lshlrev_b32_e32 v53, 2, v12
	v_xor_b32_e32 v12, 2, v231
	v_cmp_lt_i32_e32 vcc, v12, v14
	v_lshlrev_b32_e32 v7, 4, v5
	v_lshlrev_b32_e32 v5, 6, v5
	v_cndmask_b32_e32 v12, v231, v12, vcc
	v_lshlrev_b32_e32 v54, 2, v12
	v_xor_b32_e32 v12, 4, v231
	v_cmp_lt_i32_e32 vcc, v12, v14
	v_readlane_b32 s8, v255, 31
	s_movk_i32 s7, 0x110
	v_cndmask_b32_e32 v12, v231, v12, vcc
	v_lshlrev_b32_e32 v55, 2, v12
	v_xor_b32_e32 v12, 8, v231
	v_cmp_lt_i32_e32 vcc, v12, v14
	v_and_b32_e32 v15, 7, v32
	v_lshlrev_b32_e32 v17, 5, v15
	v_cndmask_b32_e32 v12, v231, v12, vcc
	v_lshlrev_b32_e32 v56, 2, v12
	v_and_b32_e32 v12, 0xffffff00, v32
	v_add3_u32 v5, s8, v12, v5
	v_ashrrev_i32_e32 v12, 3, v32
	v_mul_lo_u32 v16, v12, s7
	v_add3_u32 v57, 0, v16, v17
	v_xor_b32_e32 v17, 32, v231
	v_cmp_lt_i32_e32 vcc, v17, v14
	v_lshlrev_b32_e32 v4, 4, v32
	v_and_b32_e32 v166, 0xf0, v4
	v_cndmask_b32_e32 v17, v231, v17, vcc
	v_lshlrev_b32_e32 v67, 2, v17
	v_xor_b32_e32 v17, 16, v231
	v_cmp_lt_i32_e32 vcc, v17, v14
	s_load_dwordx2 s[88:89], s[0:1], 0xf0
	s_load_dwordx2 s[86:87], s[0:1], 0x98
	v_cndmask_b32_e32 v14, v231, v17, vcc
	v_lshlrev_b32_e32 v68, 2, v14
	v_add_u32_e32 v14, -1, v231
	v_cmp_lt_i32_e32 vcc, v14, v13
	v_add_u32_e32 v4, 0, v166
	s_mov_b32 s15, 0xd000
	v_cndmask_b32_e32 v14, v14, v231, vcc
	v_lshlrev_b32_e32 v70, 2, v14
	v_add_u32_e32 v14, -2, v231
	v_cmp_lt_i32_e32 vcc, v14, v13
	v_and_b32_e32 v34, 63, v32
	v_and_b32_e32 v0, 15, v32
	v_cndmask_b32_e32 v14, v14, v231, vcc
	v_lshlrev_b32_e32 v71, 2, v14
	v_add_u32_e32 v14, -4, v231
	v_cmp_lt_i32_e32 vcc, v14, v13
	v_and_b32_e32 v9, 48, v32
	v_lshrrev_b32_e32 v10, 2, v32
	v_cndmask_b32_e32 v14, v14, v231, vcc
	v_lshlrev_b32_e32 v72, 2, v14
	v_add_u32_e32 v14, -8, v231
	v_cmp_lt_i32_e32 vcc, v14, v13
	v_readlane_b32 s3, v255, 32
	v_mul_u32_u24_e32 v2, 0x88, v34
	v_cndmask_b32_e32 v14, v14, v231, vcc
	v_lshlrev_b32_e32 v73, 2, v14
	v_add_u32_e32 v14, -16, v231
	v_cmp_lt_i32_e32 vcc, v14, v13
	v_or_b32_e32 v8, v7, v0
	v_add_u32_e32 v35, 0, v9
	v_cndmask_b32_e32 v14, v14, v231, vcc
	v_lshlrev_b32_e32 v74, 2, v14
	v_subrev_u32_e32 v14, 32, v231
	v_cmp_lt_i32_e32 vcc, v14, v13
	v_and_b32_e32 v10, 12, v10
	v_lshl_add_u32 v58, v15, 6, s3
	v_cndmask_b32_e32 v13, v14, v231, vcc
	v_add_u32_e32 v14, 0x200, v32
	v_ashrrev_i32_e32 v17, 3, v14
	v_ashrrev_i32_e32 v14, 4, v14
	v_lshlrev_b32_e32 v42, 7, v14
	v_mul_lo_u32 v14, v14, s7
	v_add3_u32 v79, v4, v14, s15
	v_add_u32_e32 v14, 0x400, v32
	v_ashrrev_i32_e32 v14, 4, v14
	v_lshlrev_b32_e32 v44, 7, v14
	v_mul_lo_u32 v14, v14, s7
	v_lshl_add_u32 v64, v32, 2, s3
	s_movk_i32 s3, 0x1080
	v_ashrrev_i32_e32 v18, 4, v32
	v_add3_u32 v80, v4, v14, s15
	v_add_u32_e32 v14, 0x600, v32
	s_waitcnt lgkmcnt(0)
	s_add_u32 s5, s88, 0x5190000
	v_lshl_add_u32 v2, v2, 1, 0
	s_movk_i32 s2, 0xfef2
	v_ashrrev_i32_e32 v6, 8, v32
	v_mad_u32_u24 v52, v8, s7, v35
	v_or_b32_e32 v11, v7, v10
	v_mul_u32_u24_e32 v8, 0x90, v8
	v_readlane_b32 s9, v255, 33
	v_lshlrev_b32_e32 v66, 3, v1
	v_mul_lo_u32 v1, v1, s3
	s_movk_i32 s3, 0x90
	v_lshlrev_b32_e32 v40, 7, v18
	v_mul_lo_u32 v18, v18, s7
	v_ashrrev_i32_e32 v14, 4, v14
	v_mov_b32_e32 v22, 0x120
	s_addc_u32 s6, s89, 0
	v_mad_i32_i24 v3, v34, s2, v2
	v_cmp_eq_u32_e64 s[44:45], 0, v0
	v_add3_u32 v59, s9, v8, v9
	v_lshl_or_b32 v8, v6, 6, v0
	s_add_i32 s2, 0, 0x20000
	v_add3_u32 v78, v4, v18, s15
	v_lshlrev_b32_e32 v46, 7, v14
	v_mul_lo_u32 v14, v14, s7
	v_lshl_or_b32 v0, v6, 5, v0
	v_or_b32_e32 v18, 1, v11
	v_or_b32_e32 v20, 2, v11
	v_mad_u32_u24 v89, v11, s3, v22
	v_or_b32_e32 v22, 3, v11
	v_readlane_b32 s10, v255, 34
	v_readlane_b32 s11, v255, 35
	v_readlane_b32 s12, v255, 36
	v_readlane_b32 s13, v255, 37
	v_add3_u32 v81, v4, v14, s15
	v_mul_lo_u32 v4, v0, s7
	v_or_b32_e32 v6, 16, v0
	v_lshl_add_u32 v82, v0, 2, s2
	v_lshl_add_u32 v83, v0, 1, s9
	v_cmp_le_i32_e64 s[60:61], v0, v11
	v_cmp_le_i32_e64 s[62:63], v0, v18
	v_cmp_le_i32_e64 s[64:65], v0, v20
	v_cmp_le_i32_e64 s[66:67], v0, v22
	v_lshlrev_b32_e32 v0, 2, v22
	v_add_u32_e32 v90, s10, v0
	v_mov_b32_e32 v23, 0x1b0
	s_waitcnt vmcnt(0)
;   __host__ __device__ __forceinline__ bf16_t* ACT() const { return (bf16_t*)(wsl() + OFF_ACT); }
; __device__ __forceinline__ void m3_phase(const Params& p, char* smem) {
;     ...
; #pragma unroll
;       for (int i = 0; i < 2; ++i) {
;         int idx = tid + i * NTHR;
;         int r = idx & 63, fc = (idx >> 6) * 8;
;         int row = rowbase + mchunk_tok(dir, j, r);
;         const bf16_t* src = p.ACT() + (size_t)row * PW;
;         uint4 qv = *(const uint4*)(src + 672 + h * 128 + fc);
;         uint4 kv = *(const uint4*)(src + 1184 + h * 128 + fc);
;         uint4 vv = *(const uint4*)(src + 1696 + h * 128 + fc);
;         *(uint4*)(Qs + r * 136 + fc) = qv;
;         *(uint4*)(Ks + r * 136 + fc) = kv;
	v_add_u32_e32 v113, s11, v0
	v_add_u32_e32 v114, s12, v0
	v_add_u32_e32 v115, s13, v0
	v_add_u32_e32 v116, s8, v0
	v_bitop3_b32 v0, v7, 60, v10 bitop3:0x36
	v_cmp_eq_u32_e64 s[46:47], 0, v15
	v_lshlrev_b32_e32 v15, 2, v34
	v_readlane_b32 s14, v255, 38
	v_mad_u32_u24 v91, v11, s3, v23
	v_lshl_add_u32 v92, v6, 2, s2
	v_cmp_le_i32_e64 s[68:69], v6, v11
	v_lshlrev_b32_e32 v23, 1, v6
	v_cmp_le_i32_e64 s[70:71], v6, v18
	v_cmp_le_i32_e64 s[72:73], v6, v20
	v_cmp_le_i32_e64 s[74:75], v6, v22
	v_mul_lo_u32 v6, v8, s3
	v_mul_lo_u32 v97, v8, s7
	v_lshlrev_b32_e32 v8, 2, v8
	v_mul_u32_u24_e32 v0, 0x210, v0
	v_add_u32_e32 v60, s2, v15
	v_add3_u32 v121, s14, v0, v8
	v_or_b32_e32 v0, 1, v66
	s_movk_i32 s2, 0x210
	v_add_u32_e32 v16, s14, v15
	v_mul_lo_u32 v0, v0, s2
	v_add_u32_e32 v69, v16, v1
	v_add3_u32 v122, s14, v1, v15
	v_add_u32_e32 v1, 0x210, v0
	v_add_u32_e32 v125, v16, v1
	v_add3_u32 v126, s14, v1, v15
	v_add_u32_e32 v1, 0x420, v0
	v_add_u32_e32 v127, v16, v1
	v_add3_u32 v128, s14, v1, v15
	v_add_u32_e32 v1, 0x630, v0
	s_add_u32 s90, s88, 0x7290000
	v_add_u32_e32 v129, v16, v1
	v_add3_u32 v130, s14, v1, v15
	v_add_u32_e32 v1, 0x840, v0
	s_addc_u32 s91, s89, 0
	v_lshl_add_u32 v65, v12, 2, s13
	v_and_b32_e32 v36, -8, v12
	v_or_b32_e32 v12, 7, v12
	v_and_b32_e32 v38, -8, v17
	v_or_b32_e32 v17, 7, v17
	v_lshlrev_b32_e32 v14, 2, v11
	v_mul_u32_u24_e32 v85, 0x90, v11
	v_lshlrev_b32_e32 v19, 2, v18
	v_mad_u32_u24 v87, v11, s3, s3
	v_mul_u32_u24_e32 v11, 0x210, v11
	v_add_u32_e32 v123, v16, v0
	v_add3_u32 v124, s14, v0, v15
	v_add_u32_e32 v131, v16, v1
	v_add3_u32 v132, s14, v1, v15
	v_add_u32_e32 v1, 0xa50, v0
	v_add_u32_e32 v0, 0xc60, v0
	s_add_u32 s92, s88, 0x11186000
	v_ashrrev_i32_e32 v33, 31, v32
	v_lshlrev_b32_e32 v75, 2, v13
	v_lshl_add_u32 v76, v36, 1, v2
	v_mul_lo_u32 v13, v36, s3
	v_mul_lo_u32 v12, v12, s3
	v_lshl_add_u32 v77, v38, 1, v2
	v_lshrrev_b32_e32 v208, 4, v32
	v_and_b32_e32 v209, 15, v32
	v_lshlrev_b32_e32 v209, 4, v209
	v_sub_u32_e32 v210, v208, v34
	v_mul_i32_i24_e32 v210, 0x1600, v210
	v_add_u32_e32 v196, v210, v209
	v_ashrrev_i32_e32 v197, 31, v196
	v_add_u32_e32 v198, 0x2c000, v196
	v_ashrrev_i32_e32 v199, 31, v198
	v_sub_u32_e32 v200, v209, v210
	v_ashrrev_i32_e32 v201, 31, v200
	v_add_u32_e32 v202, 0xfffd4000, v200
	v_ashrrev_i32_e32 v203, 31, v202
	v_mul_u32_u24_e32 v206, 0x110, v208
	v_add_u32_e32 v206, v206, v209
	v_add_u32_e32 v207, 0x2200, v206
	v_mul_lo_u32 v2, v38, s3
	v_mul_lo_u32 v17, v17, s3
	v_add_u32_e32 v84, s10, v14
	v_add_u32_e32 v86, s10, v19
	v_add_u32_e32 v98, s11, v14
	v_add_u32_e32 v99, s8, v14
	v_add_u32_e32 v100, s13, v14
	v_add_u32_e32 v101, s12, v14
	v_bitop3_b32 v14, v7, 63, v10 bitop3:0x36
	v_add3_u32 v102, s14, v11, v8
	v_add_u32_e32 v103, s11, v19
	v_add_u32_e32 v104, s12, v19
	v_add_u32_e32 v105, s13, v19
	v_add_u32_e32 v106, s8, v19
	v_bitop3_b32 v11, v7, 62, v10 bitop3:0x36
	v_bitop3_b32 v19, v7, 61, v10 bitop3:0x36
	v_add_u32_e32 v133, v16, v1
	v_add3_u32 v134, s14, v1, v15
	v_add_u32_e32 v135, v16, v0
	v_add3_u32 v136, s14, v0, v15
	v_lshl_add_u64 v[0:1], s[88:89], 0, v[166:167]
	s_mov_b64 s[2:3], 0xcd50000
	s_addc_u32 s93, s89, 0
	v_lshlrev_b32_e32 v21, 2, v20
	v_add_u32_e32 v18, 0x1100, v97
	v_mul_u32_u24_e32 v14, 0x210, v14
	v_mul_u32_u24_e32 v11, 0x210, v11
	v_mul_u32_u24_e32 v19, 0x210, v19
	v_lshl_add_u64 v[48:49], v[0:1], 0, s[2:3]
	s_add_u32 s7, s88, 0x115cb200
	v_lshl_add_u64 v[0:1], v[32:33], 2, s[88:89]
	s_mov_b64 s[2:3], 0x114bf000
	v_cmp_lt_u32_e64 s[40:41], 63, v32
	v_cmp_gt_i32_e64 s[42:43], s85, v32
	v_add_u32_e32 v61, s10, v15
	v_add_u32_e32 v62, s11, v15
	v_add_u32_e32 v63, s12, v15
	v_cmp_eq_u32_e64 s[48:49], 0, v34
	v_cmp_gt_u32_e64 s[50:51], 2, v34
	v_cmp_gt_u32_e64 s[52:53], 4, v34
	v_cmp_gt_u32_e64 s[54:55], 8, v34
	v_cmp_gt_u32_e64 s[56:57], 16, v34
	v_cmp_gt_u32_e64 s[58:59], 32, v34
	v_ashrrev_i32_e32 v37, 31, v36
	v_ashrrev_i32_e32 v39, 31, v38
	v_ashrrev_i32_e32 v41, 31, v40
	v_ashrrev_i32_e32 v43, 31, v42
	v_ashrrev_i32_e32 v45, 31, v44
	v_ashrrev_i32_e32 v47, 31, v46
	v_add_u32_e32 v88, s10, v21
	v_add3_u32 v93, s9, v85, v23
	v_add3_u32 v94, s9, v87, v23
	v_add3_u32 v95, s9, v89, v23
	v_add3_u32 v96, s9, v91, v23
	v_add_u32_e32 v107, 0x210, v102
	v_add_u32_e32 v108, s11, v21
	v_add_u32_e32 v109, s12, v21
	v_add_u32_e32 v110, s13, v21
	v_add_u32_e32 v111, s8, v21
	v_add_u32_e32 v112, 0x420, v102
	v_add_u32_e32 v117, 0x630, v102
	v_add3_u32 v118, s14, v14, v8
	v_add3_u32 v119, s14, v11, v8
	v_add3_u32 v120, s14, v19, v8
	s_addc_u32 s8, s89, 0
	v_lshl_add_u64 v[50:51], v[0:1], 0, s[2:3]
	s_lshl_b32 s9, s4, 6
	s_sub_i32 s10, 0, s4
	v_lshlrev_b32_e32 v166, 1, v34
	v_add_u32_e32 v33, v3, v13
	v_add_u32_e32 v137, v3, v12
	v_add_u32_e32 v138, v3, v2
	v_add_u32_e32 v139, v3, v17
	v_add_u32_e32 v140, v35, v4
	v_add_u32_e32 v141, v5, v9
	v_add_u32_e32 v142, v35, v6
	v_add_u32_e32 v143, v35, v18
	v_mov_b32_e32 v144, v34
	v_mov_b32_e32 v145, v32
	s_branch .LBB0_485

;   __host__ __device__ __forceinline__ bf16_t* ACT() const { return (bf16_t*)(wsl() + OFF_ACT); }
; #define MFMA16(a, b, c) __builtin_amdgcn_mfma_f32_16x16x32_bf16(a, b, c, 0, 0, 0)
; __device__ __forceinline__ void m3_phase(const Params& p, char* smem) {
;     ...
; #pragma unroll
;       for (int i = 0; i < 2; ++i) {
;         int idx = tid + i * NTHR;
;         int r = idx & 63, fc = (idx >> 6) * 8;
;         int row = rowbase + mchunk_tok(dir, j, r);
;         const bf16_t* src = p.ACT() + (size_t)row * PW;
;         uint4 qv = *(const uint4*)(src + 672 + h * 128 + fc);
;         uint4 kv = *(const uint4*)(src + 1184 + h * 128 + fc);
;         uint4 vv = *(const uint4*)(src + 1696 + h * 128 + fc);
;         *(uint4*)(Qs + r * 136 + fc) = qv;
;         *(uint4*)(Ks + r * 136 + fc) = kv;
;     ...
;       {
;         const int mi = w & 3, nb2 = (w >> 2) * 2;
;         f32x4 s2[2] = {(f32x4){0.f, 0.f, 0.f, 0.f}, (f32x4){0.f, 0.f, 0.f, 0.f}};
; #pragma unroll
;         for (int ks = 0; ks < 4; ++ks) {
;           bf16x8 a = *(const bf16x8*)(Qs + (mi * 16 + fr) * 136 + ks * 32 + fq * 8);
; #pragma unroll
;           for (int q = 0; q < 2; ++q) {
;             bf16x8 bb = *(const bf16x8*)(Ks + ((nb2 + q) * 16 + fr) * 136 + ks * 32 + fq * 8);
;             s2[q] = MFMA16(a, bb, s2[q]);
;           }
;         }
.LBB0_491:
	s_or_b64 exec, exec, s[2:3]
	s_sub_i32 s11, s12, s11
	s_add_i32 s11, s11, s9
	v_add_u32_e32 v4, s11, v144
	v_mov_b64_e32 v[2:3], s[90:91]
	v_mad_i64_i32 v[2:3], s[2:3], v4, s84, v[2:3]
	s_lshl_b32 s30, s13, 8
	v_lshl_add_u64 v[14:15], v[2:3], 0, s[30:31]
	v_lshl_add_u64 v[10:11], v[36:37], 1, v[14:15]
	v_lshl_add_u64 v[204:205], v[14:15], 0, v[196:197]
	global_load_dwordx4 v[2:5], v[204:205], off offset:1344
	global_load_dwordx4 v[6:9], v[204:205], off offset:2368
	s_nop 0
	global_load_dwordx4 v[10:13], v[10:11], off offset:3392
	v_lshlrev_b64 v[0:1], 15, v[0:1]
	s_waitcnt vmcnt(2)
	ds_write_b128 v206, v[2:5]
	s_waitcnt vmcnt(1)
	ds_write_b128 v206, v[6:9] offset:17408
	s_waitcnt vmcnt(0)
	ds_write_b16 v33, v10 offset:34816
	ds_write_b16_d16_hi v33, v10 offset:34960
	ds_write_b16 v33, v11 offset:35104
	ds_write_b16_d16_hi v33, v11 offset:35248
	ds_write_b16 v33, v12 offset:35392
	ds_write_b16_d16_hi v33, v12 offset:35536
	ds_write_b16 v33, v13 offset:35680
	ds_write_b16_d16_hi v137, v13 offset:34816
	v_lshl_add_u64 v[10:11], v[38:39], 1, v[14:15]
	v_lshl_add_u64 v[204:205], v[14:15], 0, v[198:199]
	global_load_dwordx4 v[2:5], v[204:205], off offset:1344
	global_load_dwordx4 v[6:9], v[204:205], off offset:2368
	s_nop 0
	global_load_dwordx4 v[10:13], v[10:11], off offset:3392
	s_waitcnt vmcnt(2)
	ds_write_b128 v207, v[2:5]
	s_waitcnt vmcnt(1)
	ds_write_b128 v207, v[6:9] offset:17408
	s_waitcnt vmcnt(0)
	ds_write_b16 v138, v10 offset:34816
	ds_write_b16_d16_hi v138, v10 offset:34960
	ds_write_b16 v138, v11 offset:35104
	ds_write_b16_d16_hi v138, v11 offset:35248
	ds_write_b16 v138, v12 offset:35392
	ds_write_b16_d16_hi v138, v12 offset:35536
	ds_write_b16 v138, v13 offset:35680
	ds_write_b16_d16_hi v139, v13 offset:34816
	v_lshl_add_u64 v[4:5], v[48:49], 0, v[0:1]
	v_lshl_add_u64 v[0:1], v[40:41], 1, v[4:5]
	global_load_dwordx4 v[0:3], v[0:1], off
	s_waitcnt vmcnt(0)
	ds_write_b128 v78, v[0:3]
	v_lshl_add_u64 v[0:1], v[42:43], 1, v[4:5]
	global_load_dwordx4 v[0:3], v[0:1], off
	s_waitcnt vmcnt(0)
	ds_write_b128 v79, v[0:3]
	v_lshl_add_u64 v[0:1], v[44:45], 1, v[4:5]
	global_load_dwordx4 v[0:3], v[0:1], off
	s_waitcnt vmcnt(0)
	ds_write_b128 v80, v[0:3]
	v_lshl_add_u64 v[0:1], v[46:47], 1, v[4:5]
	global_load_dwordx4 v[0:3], v[0:1], off
	s_waitcnt vmcnt(0)
	ds_write_b128 v81, v[0:3]
	s_waitcnt lgkmcnt(0)
	s_barrier
	ds_read_b128 v[0:3], v52
	ds_read_b128 v[4:7], v140 offset:17408
	ds_read_b128 v[8:11], v140 offset:21760
	s_waitcnt lgkmcnt(1)
	v_mfma_f32_16x16x32_bf16 v[4:7], v[0:3], v[4:7], 0
	s_waitcnt lgkmcnt(0)
	v_mfma_f32_16x16x32_bf16 v[0:3], v[0:3], v[8:11], 0
	ds_read_b128 v[8:11], v52 offset:64
	ds_read_b128 v[12:15], v140 offset:17472
	s_waitcnt lgkmcnt(0)
	v_mfma_f32_16x16x32_bf16 v[4:7], v[8:11], v[12:15], v[4:7]
	ds_read_b128 v[12:15], v140 offset:21824
	s_waitcnt lgkmcnt(0)
	v_mfma_f32_16x16x32_bf16 v[0:3], v[8:11], v[12:15], v[0:3]
	ds_read_b128 v[8:11], v52 offset:128
	ds_read_b128 v[12:15], v140 offset:17536
	s_waitcnt lgkmcnt(0)
	v_mfma_f32_16x16x32_bf16 v[4:7], v[8:11], v[12:15], v[4:7]
	ds_read_b128 v[12:15], v140 offset:21888
	s_waitcnt lgkmcnt(0)
	v_mfma_f32_16x16x32_bf16 v[0:3], v[8:11], v[12:15], v[0:3]
	ds_read_b128 v[8:11], v52 offset:192
	ds_read_b128 v[12:15], v140 offset:17600
	s_waitcnt lgkmcnt(0)
	v_mfma_f32_16x16x32_bf16 v[4:7], v[8:11], v[12:15], v[4:7]
	ds_read_b128 v[12:15], v140 offset:21952
	s_waitcnt lgkmcnt(0)
	v_mfma_f32_16x16x32_bf16 v[0:3], v[8:11], v[12:15], v[0:3]
	ds_read_b32 v10, v82
	v_mov_b32_e32 v11, 0
	v_mov_b32_e32 v8, 0
	s_and_saveexec_b64 s[2:3], s[60:61]
	s_cbranch_execz .LBB0_493
	ds_read_b32 v8, v84
	s_waitcnt lgkmcnt(0)
	v_add_f32_e32 v8, v10, v8
	v_mul_f32_e32 v8, 0x3fb8aa3b, v8
	v_exp_f32_e32 v8, v8

;   __host__ __device__ __forceinline__ bf16_t* ACT() const { return (bf16_t*)(wsl() + OFF_ACT); }
; #define MFMA16(a, b, c) __builtin_amdgcn_mfma_f32_16x16x32_bf16(a, b, c, 0, 0, 0)
; __device__ __forceinline__ void m3_phase(const Params& p, char* smem) {
;     ...
; #pragma unroll
;       for (int i = 0; i < 2; ++i) {
;         int idx = tid + i * NTHR;
;         int r = idx & 63, fc = (idx >> 6) * 8;
;         int row = rowbase + mchunk_tok(dir, j, r);
;         const bf16_t* src = p.ACT() + (size_t)row * PW;
;         uint4 qv = *(const uint4*)(src + 672 + h * 128 + fc);
;         uint4 kv = *(const uint4*)(src + 1184 + h * 128 + fc);
;         uint4 vv = *(const uint4*)(src + 1696 + h * 128 + fc);
;         *(uint4*)(Qs + r * 136 + fc) = qv;
;         *(uint4*)(Ks + r * 136 + fc) = kv;
;     ...
;       {
;         const int mi = w & 3, nb2 = (w >> 2) * 2;
;         f32x4 s2[2] = {(f32x4){0.f, 0.f, 0.f, 0.f}, (f32x4){0.f, 0.f, 0.f, 0.f}};
; #pragma unroll
;         for (int ks = 0; ks < 4; ++ks) {
;           bf16x8 a = *(const bf16x8*)(Qs + (mi * 16 + fr) * 136 + ks * 32 + fq * 8);
; #pragma unroll
;           for (int q = 0; q < 2; ++q) {
;             bf16x8 bb = *(const bf16x8*)(Ks + ((nb2 + q) * 16 + fr) * 136 + ks * 32 + fq * 8);
;             s2[q] = MFMA16(a, bb, s2[q]);
;           }
;         }
.LBB0_523:
	s_or_b64 exec, exec, s[2:3]
	v_or_b32_e32 v2, s14, v34
	s_lshl_b32 s13, s13, 7
	v_xad_u32 v4, v2, 63, s12
	v_mov_b64_e32 v[2:3], s[90:91]
	v_mad_i64_i32 v[2:3], s[2:3], v4, s84, v[2:3]
	s_lshl_b32 s30, s13, 1
	v_lshl_add_u64 v[14:15], v[2:3], 0, s[30:31]
	v_lshl_add_u64 v[10:11], v[36:37], 1, v[14:15]
	v_lshl_add_u64 v[204:205], v[14:15], 0, v[200:201]
	global_load_dwordx4 v[2:5], v[204:205], off offset:1344
	global_load_dwordx4 v[6:9], v[204:205], off offset:2368
	s_nop 0
	global_load_dwordx4 v[10:13], v[10:11], off offset:3392
	v_lshlrev_b64 v[0:1], 15, v[0:1]
	s_waitcnt vmcnt(2)
	ds_write_b128 v206, v[2:5]
	s_waitcnt vmcnt(1)
	ds_write_b128 v206, v[6:9] offset:17408
	s_waitcnt vmcnt(0)
	ds_write_b16 v33, v10 offset:34816
	ds_write_b16_d16_hi v33, v10 offset:34960
	ds_write_b16 v33, v11 offset:35104
	ds_write_b16_d16_hi v33, v11 offset:35248
	ds_write_b16 v33, v12 offset:35392
	ds_write_b16_d16_hi v33, v12 offset:35536
	ds_write_b16 v33, v13 offset:35680
	ds_write_b16_d16_hi v137, v13 offset:34816
	v_lshl_add_u64 v[10:11], v[38:39], 1, v[14:15]
	v_lshl_add_u64 v[204:205], v[14:15], 0, v[202:203]
	global_load_dwordx4 v[2:5], v[204:205], off offset:1344
	global_load_dwordx4 v[6:9], v[204:205], off offset:2368
	s_nop 0
	global_load_dwordx4 v[10:13], v[10:11], off offset:3392
	s_waitcnt vmcnt(2)
	ds_write_b128 v207, v[2:5]
	s_waitcnt vmcnt(1)
	ds_write_b128 v207, v[6:9] offset:17408
	s_waitcnt vmcnt(0)
	ds_write_b16 v138, v10 offset:34816
	ds_write_b16_d16_hi v138, v10 offset:34960
	ds_write_b16 v138, v11 offset:35104
	ds_write_b16_d16_hi v138, v11 offset:35248
	ds_write_b16 v138, v12 offset:35392
	ds_write_b16_d16_hi v138, v12 offset:35536
	ds_write_b16 v138, v13 offset:35680
	ds_write_b16_d16_hi v139, v13 offset:34816
	v_lshl_add_u64 v[4:5], v[48:49], 0, v[0:1]
	v_lshl_add_u64 v[0:1], v[40:41], 1, v[4:5]
	global_load_dwordx4 v[0:3], v[0:1], off
	s_waitcnt vmcnt(0)
	ds_write_b128 v78, v[0:3]
	v_lshl_add_u64 v[0:1], v[42:43], 1, v[4:5]
	global_load_dwordx4 v[0:3], v[0:1], off
	s_waitcnt vmcnt(0)
	ds_write_b128 v79, v[0:3]
	v_lshl_add_u64 v[0:1], v[44:45], 1, v[4:5]
	global_load_dwordx4 v[0:3], v[0:1], off
	s_waitcnt vmcnt(0)
	ds_write_b128 v80, v[0:3]
	v_lshl_add_u64 v[0:1], v[46:47], 1, v[4:5]
	global_load_dwordx4 v[0:3], v[0:1], off
	s_waitcnt vmcnt(0)
	ds_write_b128 v81, v[0:3]
	s_waitcnt lgkmcnt(0)
	s_barrier
	ds_read_b128 v[0:3], v52
	ds_read_b128 v[4:7], v140 offset:17408
	ds_read_b128 v[8:11], v140 offset:21760
	s_waitcnt lgkmcnt(1)
	v_mfma_f32_16x16x32_bf16 v[4:7], v[0:3], v[4:7], 0
	s_waitcnt lgkmcnt(0)
	v_mfma_f32_16x16x32_bf16 v[0:3], v[0:3], v[8:11], 0
	ds_read_b128 v[8:11], v52 offset:64
	ds_read_b128 v[12:15], v140 offset:17472
	s_waitcnt lgkmcnt(0)
	v_mfma_f32_16x16x32_bf16 v[4:7], v[8:11], v[12:15], v[4:7]
	ds_read_b128 v[12:15], v140 offset:21824
	s_waitcnt lgkmcnt(0)
	v_mfma_f32_16x16x32_bf16 v[0:3], v[8:11], v[12:15], v[0:3]
	ds_read_b128 v[8:11], v52 offset:128
	ds_read_b128 v[12:15], v140 offset:17536
	s_waitcnt lgkmcnt(0)
	v_mfma_f32_16x16x32_bf16 v[4:7], v[8:11], v[12:15], v[4:7]
	ds_read_b128 v[12:15], v140 offset:21888
	s_waitcnt lgkmcnt(0)
	v_mfma_f32_16x16x32_bf16 v[0:3], v[8:11], v[12:15], v[0:3]
	ds_read_b128 v[8:11], v52 offset:192
	ds_read_b128 v[12:15], v140 offset:17600
	s_waitcnt lgkmcnt(0)
	v_mfma_f32_16x16x32_bf16 v[4:7], v[8:11], v[12:15], v[4:7]
	ds_read_b128 v[12:15], v140 offset:21952
	s_waitcnt lgkmcnt(0)
	v_mfma_f32_16x16x32_bf16 v[0:3], v[8:11], v[12:15], v[0:3]
	ds_read_b32 v10, v82
	v_mov_b32_e32 v11, 0
	v_mov_b32_e32 v8, 0
	s_and_saveexec_b64 s[2:3], s[60:61]
	s_cbranch_execz .LBB0_525
	ds_read_b32 v8, v84
	s_waitcnt lgkmcnt(0)
	v_add_f32_e32 v8, v10, v8
	v_mul_f32_e32 v8, 0x3fb8aa3b, v8
	v_exp_f32_e32 v8, v8
